# attention: -mhat folded into QK MFMA C operand (no per-score v_sub); adaLN MOD loop 3-deep prefetch + scalar fmac; G4->G5 grid barrier skipped
# speedup vs baseline: 1.0340x; 1.0340x over previous
.LBB0_64:
	s_mul_hi_i32 s4, s24, 0x38e38e39
	s_lshr_b32 s5, s4, 31
	s_ashr_i32 s4, s4, 5
	s_add_i32 s12, s4, s5
	s_mul_i32 s4, s12, 0x90
	s_sub_i32 s4, s24, s4
	v_lshl_or_b32 v2, s4, 6, v18
	s_mul_i32 s4, s12, 0x2400000
	s_mul_hi_i32 s5, s12, 0x2400000
	s_add_u32 s4, s19, s4
	v_ashrrev_i32_e32 v3, 31, v2
	s_addc_u32 s5, s20, s5
	v_mov_b32_e32 v6, 0
	v_lshl_add_u64 v[4:5], v[2:3], 2, s[4:5]
	s_mov_b32 s10, 0
	v_mov_b32_e32 v7, v6
	v_mov_b32_e32 v8, v6
	v_mov_b32_e32 v9, v6
	v_mov_b32_e32 v10, v6
	v_mov_b32_e32 v11, v6
	v_mov_b32_e32 v12, v6
	v_mov_b32_e32 v13, v6
	v_mov_b32_e32 v14, v6
	v_mov_b32_e32 v15, v6
	v_mov_b32_e32 v16, v6
	v_mov_b32_e32 v17, v6
	v_mov_b32_e32 v20, v6
	v_mov_b32_e32 v21, v6
	v_mov_b32_e32 v22, v6
	v_mov_b32_e32 v23, v6
	v_mov_b32_e32 v24, v6
	v_mov_b32_e32 v25, v6
	v_mov_b32_e32 v26, v6
	v_mov_b32_e32 v27, v6
	v_add_co_u32_e64 v28, s[4:5], s21, v4
	s_nop 0
	s_nop 0
	v_addc_co_u32_e64 v29, s[4:5], -1, v5, s[4:5]
	v_add_co_u32_e64 v30, s[4:5], s22, v4
	s_nop 0
	s_nop 0
	v_addc_co_u32_e64 v31, s[4:5], -1, v5, s[4:5]
	v_add_co_u32_e64 v32, s[4:5], s18, v4
	s_nop 0
	s_nop 0
	v_addc_co_u32_e64 v33, s[4:5], 0, v5, s[4:5]
	global_load_dword v108, v[28:29], off
	global_load_dword v110, v[30:31], off
	global_load_dword v112, v[32:33], off
	global_load_dword v114, v[4:5], off
	v_lshl_add_u64 v[4:5], v[4:5], 0, s[8:9]
	v_add_co_u32_e64 v28, s[4:5], s21, v4
	s_nop 0
	s_nop 0
	v_addc_co_u32_e64 v29, s[4:5], -1, v5, s[4:5]
	v_add_co_u32_e64 v30, s[4:5], s22, v4
	s_nop 0
	s_nop 0
	v_addc_co_u32_e64 v31, s[4:5], -1, v5, s[4:5]
	v_add_co_u32_e64 v32, s[4:5], s18, v4
	s_nop 0
	s_nop 0
	v_addc_co_u32_e64 v33, s[4:5], 0, v5, s[4:5]
	global_load_dword v120, v[28:29], off
	global_load_dword v122, v[30:31], off
	global_load_dword v124, v[32:33], off
	global_load_dword v126, v[4:5], off
	v_lshl_add_u64 v[4:5], v[4:5], 0, s[8:9]
	v_add_co_u32_e64 v28, s[4:5], s21, v4
	s_nop 0
	s_nop 0
	v_addc_co_u32_e64 v29, s[4:5], -1, v5, s[4:5]
	v_add_co_u32_e64 v30, s[4:5], s22, v4
	s_nop 0
	s_nop 0
	v_addc_co_u32_e64 v31, s[4:5], -1, v5, s[4:5]
	v_add_co_u32_e64 v32, s[4:5], s18, v4
	s_nop 0
	s_nop 0
	v_addc_co_u32_e64 v33, s[4:5], 0, v5, s[4:5]
	global_load_dword v128, v[28:29], off
	global_load_dword v130, v[30:31], off
	global_load_dword v132, v[32:33], off
	global_load_dword v134, v[4:5], off
	v_lshl_add_u64 v[4:5], v[4:5], 0, s[8:9]
.LBB0_65:
	v_add_co_u32_e64 v28, s[4:5], s21, v4
	s_add_i32 s11, s16, s10
	s_nop 0
	v_addc_co_u32_e64 v29, s[4:5], -1, v5, s[4:5]
	v_add_co_u32_e64 v30, s[4:5], s22, v4
	v_mov_b32_e32 v19, s11
	s_nop 0
	v_addc_co_u32_e64 v31, s[4:5], -1, v5, s[4:5]
	v_add_co_u32_e64 v32, s[4:5], s18, v4
	s_add_i32 s13, s11, 0x12000
	s_nop 0
	v_addc_co_u32_e64 v33, s[4:5], 0, v5, s[4:5]
	global_load_dword v136, v[28:29], off
	global_load_dword v138, v[30:31], off
	global_load_dword v140, v[32:33], off
	global_load_dword v142, v[4:5], off
	s_add_i32 s4, s11, 0x10000
	s_add_i32 s5, s11, 0x11000
	s_add_i32 s11, s11, 0x13000
	ds_read_b128 v[28:31], v19
	ds_read_b128 v[32:35], v19 offset:4096
	ds_read_b128 v[36:39], v19 offset:8192
	ds_read_b128 v[40:43], v19 offset:12288
	ds_read_b128 v[44:47], v19 offset:16384
	ds_read_b128 v[48:51], v19 offset:20480
	ds_read_b128 v[52:55], v19 offset:24576
	ds_read_b128 v[56:59], v19 offset:28672
	ds_read_b128 v[60:63], v19 offset:32768
	ds_read_b128 v[64:67], v19 offset:36864
	ds_read_b128 v[68:71], v19 offset:40960
	ds_read_b128 v[72:75], v19 offset:45056
	ds_read_b128 v[76:79], v19 offset:49152
	ds_read_b128 v[80:83], v19 offset:53248
	ds_read_b128 v[84:87], v19 offset:57344
	ds_read_b128 v[88:91], v19 offset:61440
	v_mov_b32_e32 v19, s4
	v_mov_b32_e32 v96, s5
	v_mov_b32_e32 v100, s13
	v_mov_b32_e32 v104, s11
	ds_read_b128 v[92:95], v19
	ds_read_b128 v[96:99], v96
	ds_read_b128 v[100:103], v100
	ds_read_b128 v[104:107], v104
	s_add_i32 s10, s10, 16
	s_cmp_le_u32 s10, 0x1c0
	s_cselect_b32 s14, s8, 0
	s_cselect_b32 s15, s9, 0
	v_lshl_add_u64 v[4:5], v[4:5], 0, s[14:15]
	s_waitcnt vmcnt(12)
	s_waitcnt lgkmcnt(14)
	v_fmac_f32_e32 v8, v108, v28
	v_fmac_f32_e32 v9, v108, v32
	v_fmac_f32_e32 v8, v110, v29
	v_fmac_f32_e32 v9, v110, v33
	v_fmac_f32_e32 v8, v114, v30
	v_fmac_f32_e32 v9, v114, v34
	v_fmac_f32_e32 v8, v112, v31
	v_fmac_f32_e32 v9, v112, v35
	s_waitcnt lgkmcnt(14)
	v_fmac_f32_e32 v10, v108, v36
	v_fmac_f32_e32 v11, v108, v40
	v_fmac_f32_e32 v10, v110, v37
	v_fmac_f32_e32 v11, v110, v41
	v_fmac_f32_e32 v10, v114, v38
	v_fmac_f32_e32 v11, v114, v42
	v_fmac_f32_e32 v10, v112, v39
	v_fmac_f32_e32 v11, v112, v43
	s_waitcnt lgkmcnt(14)
	v_fmac_f32_e32 v12, v108, v44
	v_fmac_f32_e32 v13, v108, v48
	v_fmac_f32_e32 v12, v110, v45
	v_fmac_f32_e32 v13, v110, v49
	v_fmac_f32_e32 v12, v114, v46
	v_fmac_f32_e32 v13, v114, v50
	v_fmac_f32_e32 v12, v112, v47
	v_fmac_f32_e32 v13, v112, v51
	s_waitcnt lgkmcnt(12)
	v_fmac_f32_e32 v14, v108, v52
	v_fmac_f32_e32 v15, v108, v56
	v_fmac_f32_e32 v14, v110, v53
	v_fmac_f32_e32 v15, v110, v57
	v_fmac_f32_e32 v14, v114, v54
	v_fmac_f32_e32 v15, v114, v58
	v_fmac_f32_e32 v14, v112, v55
	v_fmac_f32_e32 v15, v112, v59
	s_waitcnt lgkmcnt(10)
	v_fmac_f32_e32 v16, v108, v60
	v_fmac_f32_e32 v17, v108, v64
	v_fmac_f32_e32 v16, v110, v61
	v_fmac_f32_e32 v17, v110, v65
	v_fmac_f32_e32 v16, v114, v62
	v_fmac_f32_e32 v17, v114, v66
	v_fmac_f32_e32 v16, v112, v63
	v_fmac_f32_e32 v17, v112, v67
	s_waitcnt lgkmcnt(8)
	v_fmac_f32_e32 v20, v108, v68
	v_fmac_f32_e32 v21, v108, v72
	v_fmac_f32_e32 v20, v110, v69
	v_fmac_f32_e32 v21, v110, v73
	v_fmac_f32_e32 v20, v114, v70
	v_fmac_f32_e32 v21, v114, v74
	v_fmac_f32_e32 v20, v112, v71
	v_fmac_f32_e32 v21, v112, v75
	s_waitcnt lgkmcnt(6)
	v_fmac_f32_e32 v22, v108, v76
	v_fmac_f32_e32 v23, v108, v80
	v_fmac_f32_e32 v22, v110, v77
	v_fmac_f32_e32 v23, v110, v81
	v_fmac_f32_e32 v22, v114, v78
	v_fmac_f32_e32 v23, v114, v82
	v_fmac_f32_e32 v22, v112, v79
	v_fmac_f32_e32 v23, v112, v83
	s_waitcnt lgkmcnt(4)
	v_fmac_f32_e32 v24, v108, v84
	v_fmac_f32_e32 v25, v108, v88
	v_fmac_f32_e32 v24, v110, v85
	v_fmac_f32_e32 v25, v110, v89
	v_fmac_f32_e32 v24, v114, v86
	v_fmac_f32_e32 v25, v114, v90
	v_fmac_f32_e32 v24, v112, v87
	v_fmac_f32_e32 v25, v112, v91
	s_waitcnt lgkmcnt(2)
	v_fmac_f32_e32 v26, v108, v92
	v_fmac_f32_e32 v27, v108, v96
	v_fmac_f32_e32 v26, v110, v93
	v_fmac_f32_e32 v27, v110, v97
	v_fmac_f32_e32 v26, v114, v94
	v_fmac_f32_e32 v27, v114, v98
	v_fmac_f32_e32 v26, v112, v95
	v_fmac_f32_e32 v27, v112, v99
	s_waitcnt lgkmcnt(0)
	v_fmac_f32_e32 v6, v108, v100
	v_fmac_f32_e32 v7, v108, v104
	v_fmac_f32_e32 v6, v110, v101
	v_fmac_f32_e32 v7, v110, v105
	v_fmac_f32_e32 v6, v114, v102
	v_fmac_f32_e32 v7, v114, v106
	v_fmac_f32_e32 v6, v112, v103
	v_fmac_f32_e32 v7, v112, v107
	v_add_co_u32_e64 v28, s[4:5], s21, v4
	s_add_i32 s11, s16, s10
	s_nop 0
	v_addc_co_u32_e64 v29, s[4:5], -1, v5, s[4:5]
	v_add_co_u32_e64 v30, s[4:5], s22, v4
	v_mov_b32_e32 v19, s11
	s_nop 0
	v_addc_co_u32_e64 v31, s[4:5], -1, v5, s[4:5]
	v_add_co_u32_e64 v32, s[4:5], s18, v4
	s_add_i32 s13, s11, 0x12000
	s_nop 0
	v_addc_co_u32_e64 v33, s[4:5], 0, v5, s[4:5]
	global_load_dword v108, v[28:29], off
	global_load_dword v110, v[30:31], off
	global_load_dword v112, v[32:33], off
	global_load_dword v114, v[4:5], off
	s_add_i32 s4, s11, 0x10000
	s_add_i32 s5, s11, 0x11000
	s_add_i32 s11, s11, 0x13000
	ds_read_b128 v[28:31], v19
	ds_read_b128 v[32:35], v19 offset:4096
	ds_read_b128 v[36:39], v19 offset:8192
	ds_read_b128 v[40:43], v19 offset:12288
	ds_read_b128 v[44:47], v19 offset:16384
	ds_read_b128 v[48:51], v19 offset:20480
	ds_read_b128 v[52:55], v19 offset:24576
	ds_read_b128 v[56:59], v19 offset:28672
	ds_read_b128 v[60:63], v19 offset:32768
	ds_read_b128 v[64:67], v19 offset:36864
	ds_read_b128 v[68:71], v19 offset:40960
	ds_read_b128 v[72:75], v19 offset:45056
	ds_read_b128 v[76:79], v19 offset:49152
	ds_read_b128 v[80:83], v19 offset:53248
	ds_read_b128 v[84:87], v19 offset:57344
	ds_read_b128 v[88:91], v19 offset:61440
	v_mov_b32_e32 v19, s4
	v_mov_b32_e32 v96, s5
	v_mov_b32_e32 v100, s13
	v_mov_b32_e32 v104, s11
	ds_read_b128 v[92:95], v19
	ds_read_b128 v[96:99], v96
	ds_read_b128 v[100:103], v100
	ds_read_b128 v[104:107], v104
	s_add_i32 s10, s10, 16
	s_cmp_le_u32 s10, 0x1c0
	s_cselect_b32 s14, s8, 0
	s_cselect_b32 s15, s9, 0
	v_lshl_add_u64 v[4:5], v[4:5], 0, s[14:15]
	s_waitcnt vmcnt(12)
	s_waitcnt lgkmcnt(14)
	v_fmac_f32_e32 v8, v120, v28
	v_fmac_f32_e32 v9, v120, v32
	v_fmac_f32_e32 v8, v122, v29
	v_fmac_f32_e32 v9, v122, v33
	v_fmac_f32_e32 v8, v126, v30
	v_fmac_f32_e32 v9, v126, v34
	v_fmac_f32_e32 v8, v124, v31
	v_fmac_f32_e32 v9, v124, v35
	s_waitcnt lgkmcnt(14)
	v_fmac_f32_e32 v10, v120, v36
	v_fmac_f32_e32 v11, v120, v40
	v_fmac_f32_e32 v10, v122, v37
	v_fmac_f32_e32 v11, v122, v41
	v_fmac_f32_e32 v10, v126, v38
	v_fmac_f32_e32 v11, v126, v42
	v_fmac_f32_e32 v10, v124, v39
	v_fmac_f32_e32 v11, v124, v43
	s_waitcnt lgkmcnt(14)
	v_fmac_f32_e32 v12, v120, v44
	v_fmac_f32_e32 v13, v120, v48
	v_fmac_f32_e32 v12, v122, v45
	v_fmac_f32_e32 v13, v122, v49
	v_fmac_f32_e32 v12, v126, v46
	v_fmac_f32_e32 v13, v126, v50
	v_fmac_f32_e32 v12, v124, v47
	v_fmac_f32_e32 v13, v124, v51
	s_waitcnt lgkmcnt(12)
	v_fmac_f32_e32 v14, v120, v52
	v_fmac_f32_e32 v15, v120, v56
	v_fmac_f32_e32 v14, v122, v53
	v_fmac_f32_e32 v15, v122, v57
	v_fmac_f32_e32 v14, v126, v54
	v_fmac_f32_e32 v15, v126, v58
	v_fmac_f32_e32 v14, v124, v55
	v_fmac_f32_e32 v15, v124, v59
	s_waitcnt lgkmcnt(10)
	v_fmac_f32_e32 v16, v120, v60
	v_fmac_f32_e32 v17, v120, v64
	v_fmac_f32_e32 v16, v122, v61
	v_fmac_f32_e32 v17, v122, v65
	v_fmac_f32_e32 v16, v126, v62
	v_fmac_f32_e32 v17, v126, v66
	v_fmac_f32_e32 v16, v124, v63
	v_fmac_f32_e32 v17, v124, v67
	s_waitcnt lgkmcnt(8)
	v_fmac_f32_e32 v20, v120, v68
	v_fmac_f32_e32 v21, v120, v72
	v_fmac_f32_e32 v20, v122, v69
	v_fmac_f32_e32 v21, v122, v73
	v_fmac_f32_e32 v20, v126, v70
	v_fmac_f32_e32 v21, v126, v74
	v_fmac_f32_e32 v20, v124, v71
	v_fmac_f32_e32 v21, v124, v75
	s_waitcnt lgkmcnt(6)
	v_fmac_f32_e32 v22, v120, v76
	v_fmac_f32_e32 v23, v120, v80
	v_fmac_f32_e32 v22, v122, v77
	v_fmac_f32_e32 v23, v122, v81
	v_fmac_f32_e32 v22, v126, v78
	v_fmac_f32_e32 v23, v126, v82
	v_fmac_f32_e32 v22, v124, v79
	v_fmac_f32_e32 v23, v124, v83
	s_waitcnt lgkmcnt(4)
	v_fmac_f32_e32 v24, v120, v84
	v_fmac_f32_e32 v25, v120, v88
	v_fmac_f32_e32 v24, v122, v85
	v_fmac_f32_e32 v25, v122, v89
	v_fmac_f32_e32 v24, v126, v86
	v_fmac_f32_e32 v25, v126, v90
	v_fmac_f32_e32 v24, v124, v87
	v_fmac_f32_e32 v25, v124, v91
	s_waitcnt lgkmcnt(2)
	v_fmac_f32_e32 v26, v120, v92
	v_fmac_f32_e32 v27, v120, v96
	v_fmac_f32_e32 v26, v122, v93
	v_fmac_f32_e32 v27, v122, v97
	v_fmac_f32_e32 v26, v126, v94
	v_fmac_f32_e32 v27, v126, v98
	v_fmac_f32_e32 v26, v124, v95
	v_fmac_f32_e32 v27, v124, v99
	s_waitcnt lgkmcnt(0)
	v_fmac_f32_e32 v6, v120, v100
	v_fmac_f32_e32 v7, v120, v104
	v_fmac_f32_e32 v6, v122, v101
	v_fmac_f32_e32 v7, v122, v105
	v_fmac_f32_e32 v6, v126, v102
	v_fmac_f32_e32 v7, v126, v106
	v_fmac_f32_e32 v6, v124, v103
	v_fmac_f32_e32 v7, v124, v107
	v_add_co_u32_e64 v28, s[4:5], s21, v4
	s_add_i32 s11, s16, s10
	s_nop 0
	v_addc_co_u32_e64 v29, s[4:5], -1, v5, s[4:5]
	v_add_co_u32_e64 v30, s[4:5], s22, v4
	v_mov_b32_e32 v19, s11
	s_nop 0
	v_addc_co_u32_e64 v31, s[4:5], -1, v5, s[4:5]
	v_add_co_u32_e64 v32, s[4:5], s18, v4
	s_add_i32 s13, s11, 0x12000
	s_nop 0
	v_addc_co_u32_e64 v33, s[4:5], 0, v5, s[4:5]
	global_load_dword v120, v[28:29], off
	global_load_dword v122, v[30:31], off
	global_load_dword v124, v[32:33], off
	global_load_dword v126, v[4:5], off
	s_add_i32 s4, s11, 0x10000
	s_add_i32 s5, s11, 0x11000
	s_add_i32 s11, s11, 0x13000
	ds_read_b128 v[28:31], v19
	ds_read_b128 v[32:35], v19 offset:4096
	ds_read_b128 v[36:39], v19 offset:8192
	ds_read_b128 v[40:43], v19 offset:12288
	ds_read_b128 v[44:47], v19 offset:16384
	ds_read_b128 v[48:51], v19 offset:20480
	ds_read_b128 v[52:55], v19 offset:24576
	ds_read_b128 v[56:59], v19 offset:28672
	ds_read_b128 v[60:63], v19 offset:32768
	ds_read_b128 v[64:67], v19 offset:36864
	ds_read_b128 v[68:71], v19 offset:40960
	ds_read_b128 v[72:75], v19 offset:45056
	ds_read_b128 v[76:79], v19 offset:49152
	ds_read_b128 v[80:83], v19 offset:53248
	ds_read_b128 v[84:87], v19 offset:57344
	ds_read_b128 v[88:91], v19 offset:61440
	v_mov_b32_e32 v19, s4
	v_mov_b32_e32 v96, s5
	v_mov_b32_e32 v100, s13
	v_mov_b32_e32 v104, s11
	ds_read_b128 v[92:95], v19
	ds_read_b128 v[96:99], v96
	ds_read_b128 v[100:103], v100
	ds_read_b128 v[104:107], v104
	s_add_i32 s10, s10, 16
	s_cmp_le_u32 s10, 0x1c0
	s_cselect_b32 s14, s8, 0
	s_cselect_b32 s15, s9, 0
	v_lshl_add_u64 v[4:5], v[4:5], 0, s[14:15]
	s_waitcnt vmcnt(12)
	s_waitcnt lgkmcnt(14)
	v_fmac_f32_e32 v8, v128, v28
	v_fmac_f32_e32 v9, v128, v32
	v_fmac_f32_e32 v8, v130, v29
	v_fmac_f32_e32 v9, v130, v33
	v_fmac_f32_e32 v8, v134, v30
	v_fmac_f32_e32 v9, v134, v34
	v_fmac_f32_e32 v8, v132, v31
	v_fmac_f32_e32 v9, v132, v35
	s_waitcnt lgkmcnt(14)
	v_fmac_f32_e32 v10, v128, v36
	v_fmac_f32_e32 v11, v128, v40
	v_fmac_f32_e32 v10, v130, v37
	v_fmac_f32_e32 v11, v130, v41
	v_fmac_f32_e32 v10, v134, v38
	v_fmac_f32_e32 v11, v134, v42
	v_fmac_f32_e32 v10, v132, v39
	v_fmac_f32_e32 v11, v132, v43
	s_waitcnt lgkmcnt(14)
	v_fmac_f32_e32 v12, v128, v44
	v_fmac_f32_e32 v13, v128, v48
	v_fmac_f32_e32 v12, v130, v45
	v_fmac_f32_e32 v13, v130, v49
	v_fmac_f32_e32 v12, v134, v46
	v_fmac_f32_e32 v13, v134, v50
	v_fmac_f32_e32 v12, v132, v47
	v_fmac_f32_e32 v13, v132, v51
	s_waitcnt lgkmcnt(12)
	v_fmac_f32_e32 v14, v128, v52
	v_fmac_f32_e32 v15, v128, v56
	v_fmac_f32_e32 v14, v130, v53
	v_fmac_f32_e32 v15, v130, v57
	v_fmac_f32_e32 v14, v134, v54
	v_fmac_f32_e32 v15, v134, v58
	v_fmac_f32_e32 v14, v132, v55
	v_fmac_f32_e32 v15, v132, v59
	s_waitcnt lgkmcnt(10)
	v_fmac_f32_e32 v16, v128, v60
	v_fmac_f32_e32 v17, v128, v64
	v_fmac_f32_e32 v16, v130, v61
	v_fmac_f32_e32 v17, v130, v65
	v_fmac_f32_e32 v16, v134, v62
	v_fmac_f32_e32 v17, v134, v66
	v_fmac_f32_e32 v16, v132, v63
	v_fmac_f32_e32 v17, v132, v67
	s_waitcnt lgkmcnt(8)
	v_fmac_f32_e32 v20, v128, v68
	v_fmac_f32_e32 v21, v128, v72
	v_fmac_f32_e32 v20, v130, v69
	v_fmac_f32_e32 v21, v130, v73
	v_fmac_f32_e32 v20, v134, v70
	v_fmac_f32_e32 v21, v134, v74
	v_fmac_f32_e32 v20, v132, v71
	v_fmac_f32_e32 v21, v132, v75
	s_waitcnt lgkmcnt(6)
	v_fmac_f32_e32 v22, v128, v76
	v_fmac_f32_e32 v23, v128, v80
	v_fmac_f32_e32 v22, v130, v77
	v_fmac_f32_e32 v23, v130, v81
	v_fmac_f32_e32 v22, v134, v78
	v_fmac_f32_e32 v23, v134, v82
	v_fmac_f32_e32 v22, v132, v79
	v_fmac_f32_e32 v23, v132, v83
	s_waitcnt lgkmcnt(4)
	v_fmac_f32_e32 v24, v128, v84
	v_fmac_f32_e32 v25, v128, v88
	v_fmac_f32_e32 v24, v130, v85
	v_fmac_f32_e32 v25, v130, v89
	v_fmac_f32_e32 v24, v134, v86
	v_fmac_f32_e32 v25, v134, v90
	v_fmac_f32_e32 v24, v132, v87
	v_fmac_f32_e32 v25, v132, v91
	s_waitcnt lgkmcnt(2)
	v_fmac_f32_e32 v26, v128, v92
	v_fmac_f32_e32 v27, v128, v96
	v_fmac_f32_e32 v26, v130, v93
	v_fmac_f32_e32 v27, v130, v97
	v_fmac_f32_e32 v26, v134, v94
	v_fmac_f32_e32 v27, v134, v98
	v_fmac_f32_e32 v26, v132, v95
	v_fmac_f32_e32 v27, v132, v99
	s_waitcnt lgkmcnt(0)
	v_fmac_f32_e32 v6, v128, v100
	v_fmac_f32_e32 v7, v128, v104
	v_fmac_f32_e32 v6, v130, v101
	v_fmac_f32_e32 v7, v130, v105
	v_fmac_f32_e32 v6, v134, v102
	v_fmac_f32_e32 v7, v134, v106
	v_fmac_f32_e32 v6, v132, v103
	v_fmac_f32_e32 v7, v132, v107
	v_add_co_u32_e64 v28, s[4:5], s21, v4
	s_add_i32 s11, s16, s10
	s_nop 0
	v_addc_co_u32_e64 v29, s[4:5], -1, v5, s[4:5]
	v_add_co_u32_e64 v30, s[4:5], s22, v4
	v_mov_b32_e32 v19, s11
	s_nop 0
	v_addc_co_u32_e64 v31, s[4:5], -1, v5, s[4:5]
	v_add_co_u32_e64 v32, s[4:5], s18, v4
	s_add_i32 s13, s11, 0x12000
	s_nop 0
	v_addc_co_u32_e64 v33, s[4:5], 0, v5, s[4:5]
	global_load_dword v128, v[28:29], off
	global_load_dword v130, v[30:31], off
	global_load_dword v132, v[32:33], off
	global_load_dword v134, v[4:5], off
	s_add_i32 s4, s11, 0x10000
	s_add_i32 s5, s11, 0x11000
	s_add_i32 s11, s11, 0x13000
	ds_read_b128 v[28:31], v19
	ds_read_b128 v[32:35], v19 offset:4096
	ds_read_b128 v[36:39], v19 offset:8192
	ds_read_b128 v[40:43], v19 offset:12288
	ds_read_b128 v[44:47], v19 offset:16384
	ds_read_b128 v[48:51], v19 offset:20480
	ds_read_b128 v[52:55], v19 offset:24576
	ds_read_b128 v[56:59], v19 offset:28672
	ds_read_b128 v[60:63], v19 offset:32768
	ds_read_b128 v[64:67], v19 offset:36864
	ds_read_b128 v[68:71], v19 offset:40960
	ds_read_b128 v[72:75], v19 offset:45056
	ds_read_b128 v[76:79], v19 offset:49152
	ds_read_b128 v[80:83], v19 offset:53248
	ds_read_b128 v[84:87], v19 offset:57344
	ds_read_b128 v[88:91], v19 offset:61440
	v_mov_b32_e32 v19, s4
	v_mov_b32_e32 v96, s5
	v_mov_b32_e32 v100, s13
	v_mov_b32_e32 v104, s11
	ds_read_b128 v[92:95], v19
	ds_read_b128 v[96:99], v96
	ds_read_b128 v[100:103], v100
	ds_read_b128 v[104:107], v104
	s_add_i32 s10, s10, 16
	s_cmp_le_u32 s10, 0x1c0
	s_cselect_b32 s14, s8, 0
	s_cselect_b32 s15, s9, 0
	v_lshl_add_u64 v[4:5], v[4:5], 0, s[14:15]
	s_cmpk_eq_i32 s10, 0x200
	s_waitcnt vmcnt(12)
	s_waitcnt lgkmcnt(14)
	v_fmac_f32_e32 v8, v136, v28
	v_fmac_f32_e32 v9, v136, v32
	v_fmac_f32_e32 v8, v138, v29
	v_fmac_f32_e32 v9, v138, v33
	v_fmac_f32_e32 v8, v142, v30
	v_fmac_f32_e32 v9, v142, v34
	v_fmac_f32_e32 v8, v140, v31
	v_fmac_f32_e32 v9, v140, v35
	s_waitcnt lgkmcnt(14)
	v_fmac_f32_e32 v10, v136, v36
	v_fmac_f32_e32 v11, v136, v40
	v_fmac_f32_e32 v10, v138, v37
	v_fmac_f32_e32 v11, v138, v41
	v_fmac_f32_e32 v10, v142, v38
	v_fmac_f32_e32 v11, v142, v42
	v_fmac_f32_e32 v10, v140, v39
	v_fmac_f32_e32 v11, v140, v43
	s_waitcnt lgkmcnt(14)
	v_fmac_f32_e32 v12, v136, v44
	v_fmac_f32_e32 v13, v136, v48
	v_fmac_f32_e32 v12, v138, v45
	v_fmac_f32_e32 v13, v138, v49
	v_fmac_f32_e32 v12, v142, v46
	v_fmac_f32_e32 v13, v142, v50
	v_fmac_f32_e32 v12, v140, v47
	v_fmac_f32_e32 v13, v140, v51
	s_waitcnt lgkmcnt(12)
	v_fmac_f32_e32 v14, v136, v52
	v_fmac_f32_e32 v15, v136, v56
	v_fmac_f32_e32 v14, v138, v53
	v_fmac_f32_e32 v15, v138, v57
	v_fmac_f32_e32 v14, v142, v54
	v_fmac_f32_e32 v15, v142, v58
	v_fmac_f32_e32 v14, v140, v55
	v_fmac_f32_e32 v15, v140, v59
	s_waitcnt lgkmcnt(10)
	v_fmac_f32_e32 v16, v136, v60
	v_fmac_f32_e32 v17, v136, v64
	v_fmac_f32_e32 v16, v138, v61
	v_fmac_f32_e32 v17, v138, v65
	v_fmac_f32_e32 v16, v142, v62
	v_fmac_f32_e32 v17, v142, v66
	v_fmac_f32_e32 v16, v140, v63
	v_fmac_f32_e32 v17, v140, v67
	s_waitcnt lgkmcnt(8)
	v_fmac_f32_e32 v20, v136, v68
	v_fmac_f32_e32 v21, v136, v72
	v_fmac_f32_e32 v20, v138, v69
	v_fmac_f32_e32 v21, v138, v73
	v_fmac_f32_e32 v20, v142, v70
	v_fmac_f32_e32 v21, v142, v74
	v_fmac_f32_e32 v20, v140, v71
	v_fmac_f32_e32 v21, v140, v75
	s_waitcnt lgkmcnt(6)
	v_fmac_f32_e32 v22, v136, v76
	v_fmac_f32_e32 v23, v136, v80
	v_fmac_f32_e32 v22, v138, v77
	v_fmac_f32_e32 v23, v138, v81
	v_fmac_f32_e32 v22, v142, v78
	v_fmac_f32_e32 v23, v142, v82
	v_fmac_f32_e32 v22, v140, v79
	v_fmac_f32_e32 v23, v140, v83
	s_waitcnt lgkmcnt(4)
	v_fmac_f32_e32 v24, v136, v84
	v_fmac_f32_e32 v25, v136, v88
	v_fmac_f32_e32 v24, v138, v85
	v_fmac_f32_e32 v25, v138, v89
	v_fmac_f32_e32 v24, v142, v86
	v_fmac_f32_e32 v25, v142, v90
	v_fmac_f32_e32 v24, v140, v87
	v_fmac_f32_e32 v25, v140, v91
	s_waitcnt lgkmcnt(2)
	v_fmac_f32_e32 v26, v136, v92
	v_fmac_f32_e32 v27, v136, v96
	v_fmac_f32_e32 v26, v138, v93
	v_fmac_f32_e32 v27, v138, v97
	v_fmac_f32_e32 v26, v142, v94
	v_fmac_f32_e32 v27, v142, v98
	v_fmac_f32_e32 v26, v140, v95
	v_fmac_f32_e32 v27, v140, v99
	s_waitcnt lgkmcnt(0)
	v_fmac_f32_e32 v6, v136, v100
	v_fmac_f32_e32 v7, v136, v104
	v_fmac_f32_e32 v6, v138, v101
	v_fmac_f32_e32 v7, v138, v105
	v_fmac_f32_e32 v6, v142, v102
	v_fmac_f32_e32 v7, v142, v106
	v_fmac_f32_e32 v6, v140, v103
	v_fmac_f32_e32 v7, v140, v107
	s_cbranch_scc0 .LBB0_65
	s_waitcnt vmcnt(0)
	v_add_u32_e32 v4, s17, v1
	ds_write2st64_b32 v4, v8, v9 offset1:1
	ds_write2st64_b32 v4, v10, v11 offset0:2 offset1:3
	ds_write2st64_b32 v4, v12, v13 offset0:4 offset1:5
	ds_write2st64_b32 v4, v14, v15 offset0:6 offset1:7
	ds_write2st64_b32 v4, v16, v17 offset0:8 offset1:9
	ds_write2st64_b32 v4, v20, v21 offset0:10 offset1:11
	ds_write2st64_b32 v4, v22, v23 offset0:12 offset1:13
	ds_write2st64_b32 v4, v24, v25 offset0:14 offset1:15
	ds_write2st64_b32 v4, v26, v27 offset0:16 offset1:17
	ds_write2st64_b32 v4, v6, v7 offset0:18 offset1:19
	s_waitcnt lgkmcnt(0)
	s_barrier
	s_and_saveexec_b64 s[10:11], vcc
	s_cbranch_execz .LBB0_63
	s_mul_i32 s4, s12, 0x9000
	s_mul_hi_i32 s5, s12, 0x9000
	s_add_u32 s4, s0, s4
	s_addc_u32 s5, s1, s5
	v_lshlrev_b64 v[4:5], 2, v[2:3]
	s_mul_hi_i32 s13, s12, 20
	s_mul_i32 s12, s12, 20
	v_lshl_add_u64 v[2:3], s[4:5], 0, v[4:5]
	v_lshl_add_u64 v[4:5], s[6:7], 0, v[4:5]
	s_mov_b64 s[14:15], 0
	v_mov_b32_e32 v6, v0

.LBB0_1987:
	v_lshlrev_b32_e32 v0, 1, v34
	v_and_b32_e32 v248, 32, v0
	v_lshlrev_b32_e32 v0, 4, v34
	v_and_b32_e32 v0, 0xc0, v0
	v_lshl_or_b32 v247, v243, 8, v0
	v_add_u32_e32 v0, 0, v248
	v_add3_u32 v251, v0, v245, v247
	v_max3_f32 v0, v2, v3, v18
	v_max3_f32 v34, v4, v5, v19
	s_and_b32 s20, s47, 0x3fffffc0
	v_max3_f32 v0, v0, v20, v21
	v_max3_f32 v34, v34, v8, v9
	s_lshl_b32 s20, s20, 2
	v_max3_f32 v0, v0, v6, v7
	v_max3_f32 v34, v34, v24, v25
	s_addk_i32 s19, 0x100
	v_max3_f32 v0, v0, v22, v23
	v_max3_f32 v34, v34, v12, v13
	s_add_i32 s46, s20, 0
	v_max3_f32 v0, v0, v10, v11
	v_max3_f32 v34, v34, v28, v29
	s_mov_b64 s[56:57], 0x60000
	v_max3_f32 v0, v0, v26, v27
	v_max3_f32 v34, v34, v16, v17
	s_add_i32 s46, s46, 0x12000
	v_max3_f32 v0, v0, v14, v15
	v_max3_f32 v34, v34, v32, v33
	s_lshr_b32 s51, s19, 6
	v_max3_f32 v0, v0, v30, v31
	s_waitcnt vmcnt(0) lgkmcnt(0)
	s_barrier
	s_cmp_lg_u32 0, -1
	v_max_f32_e32 v0, v0, v34
	s_mov_b64 s[20:21], 0x20000
	v_mov_b32_e32 v34, v0
	s_nop 1
	v_permlane32_swap_b32_e32 v0, v34
	v_max_f32_e32 v0, v0, v34
	s_mov_b32 s76, 1
	v_sub_f32_e32 v2, v2, v0
	v_sub_f32_e32 v3, v3, v0
	v_add_f32_e32 v249, v1, v0
	v_sub_f32_e32 v18, v18, v0
	v_sub_f32_e32 v19, v19, v0
	v_sub_f32_e32 v4, v4, v0
	s_nop 0
	v_exp_f32_e32 v96, v2
	v_exp_f32_e32 v97, v3
	v_lshl_add_u64 v[2:3], v[220:221], 0, s[56:57]
	s_mov_b32 s19, m0
	s_mov_b32 m0, s48
	s_nop 0
	global_load_lds_dwordx4 v[2:3], off
	s_mov_b32 m0, s19
	s_cselect_b32 s19, 0, 0
	s_add_i32 s18, s19, s18
	v_lshl_add_u64 v[2:3], v[222:223], 0, s[20:21]
	s_add_i32 s19, s18, 0xa000
	s_mov_b32 s20, m0
	s_mov_b32 m0, s19
	s_nop 0
	global_load_lds_dwordx4 v[2:3], off
	s_mov_b32 m0, s20
	s_mov_b64 s[20:21], 0x20080
	v_lshl_add_u64 v[2:3], v[222:223], 0, s[20:21]
	s_add_i32 s18, s18, 0xc000
	s_mov_b32 s19, m0
	s_mov_b32 m0, s18
	s_nop 0
	global_load_lds_dwordx4 v[2:3], off
	s_mov_b32 m0, s19
	ds_read_b128 v[204:207], v250 offset:8192
	ds_read_b128 v[196:199], v250 offset:8704
	ds_read_b128 v[200:203], v250 offset:10240
	ds_read_b128 v[192:195], v250 offset:10752
	ds_read_b128 v[188:191], v250 offset:12288
	ds_read_b128 v[184:187], v250 offset:12800
	ds_read_b128 v[180:183], v250 offset:14336
	ds_read_b128 v[176:179], v250 offset:14848
	v_sub_f32_e32 v20, v20, v0
	v_sub_f32_e32 v5, v5, v0
	v_sub_f32_e32 v21, v21, v0
	v_sub_f32_e32 v6, v6, v0
	v_sub_f32_e32 v22, v22, v0
	v_sub_f32_e32 v7, v7, v0
	v_sub_f32_e32 v23, v23, v0
	v_sub_f32_e32 v8, v8, v0
	v_sub_f32_e32 v24, v24, v0
	v_sub_f32_e32 v9, v9, v0
	v_sub_f32_e32 v25, v25, v0
	v_sub_f32_e32 v10, v10, v0
	v_sub_f32_e32 v26, v26, v0
	v_sub_f32_e32 v11, v11, v0
	v_sub_f32_e32 v27, v27, v0
	v_sub_f32_e32 v12, v12, v0
	v_sub_f32_e32 v28, v28, v0
	v_sub_f32_e32 v13, v13, v0
	v_sub_f32_e32 v29, v29, v0
	v_sub_f32_e32 v14, v14, v0
	v_sub_f32_e32 v30, v30, v0
	v_sub_f32_e32 v15, v15, v0
	v_sub_f32_e32 v31, v31, v0
	v_sub_f32_e32 v16, v16, v0
	v_sub_f32_e32 v32, v32, v0
	v_sub_f32_e32 v17, v17, v0
	v_sub_f32_e32 v0, v33, v0
	v_exp_f32_e32 v98, v4
	v_exp_f32_e32 v99, v5
	v_exp_f32_e32 v100, v6
	v_exp_f32_e32 v101, v7
	v_exp_f32_e32 v102, v8
	v_exp_f32_e32 v103, v9
	v_exp_f32_e32 v104, v10
	v_exp_f32_e32 v105, v11
	v_exp_f32_e32 v106, v12
	v_exp_f32_e32 v107, v13
	v_exp_f32_e32 v108, v14
	v_exp_f32_e32 v109, v15
	v_exp_f32_e32 v110, v16
	v_exp_f32_e32 v111, v17
	v_exp_f32_e32 v80, v18
	v_exp_f32_e32 v81, v19
	v_exp_f32_e32 v82, v20
	v_exp_f32_e32 v83, v21
	v_exp_f32_e32 v84, v22
	v_exp_f32_e32 v85, v23
	v_exp_f32_e32 v86, v24
	v_exp_f32_e32 v87, v25
	v_exp_f32_e32 v88, v26
	v_exp_f32_e32 v89, v27
	v_exp_f32_e32 v90, v28
	v_exp_f32_e32 v91, v29
	v_exp_f32_e32 v92, v30
	v_exp_f32_e32 v93, v31
	v_exp_f32_e32 v94, v32
	v_exp_f32_e32 v95, v0
	s_waitcnt vmcnt(3) lgkmcnt(0)
	s_barrier
	s_mov_b32 s27, 0
	s_andn2_b64 vcc, exec, s[2:3]
	v_cmp_gt_u32_e64 s[18:19], 32, v241
	v_lshlrev_b32_e32 v252, 4, v243
	v_lshl_add_u32 v246, v242, 2, s46
	s_cbranch_vccnz .LBB0_2004
	v_mov_b32_e32 v14, v1
	v_mov_b32_e32 v15, v1
	v_mov_b32_e32 v0, v1
	v_mov_b32_e32 v2, v1
	v_mov_b32_e32 v3, v1
	v_mov_b32_e32 v4, v1
	v_mov_b32_e32 v5, v1
	v_mov_b32_e32 v6, v1
	v_mov_b32_e32 v7, v1
	v_mov_b32_e32 v8, v1
	v_mov_b32_e32 v9, v1
	v_mov_b32_e32 v10, v1
	v_mov_b32_e32 v11, v1
	v_mov_b32_e32 v12, v1
	v_mov_b32_e32 v13, v1
	v_mov_b64_e32 v[78:79], v[14:15]
	v_mov_b64_e32 v[62:63], v[14:15]
	v_mov_b64_e32 v[46:47], v[14:15]
	v_mov_b64_e32 v[30:31], v[14:15]
	s_mov_b32 s20, 0
	s_movk_i32 s27, 0x4000
	s_movk_i32 s29, 0x2000
	v_mov_b32_e32 v237, 0
	s_mov_b32 s28, 6
	s_mov_b64 s[2:3], 0
	v_mov_b64_e32 v[76:77], v[12:13]
	v_mov_b64_e32 v[74:75], v[10:11]
	v_mov_b64_e32 v[72:73], v[8:9]
	v_mov_b64_e32 v[70:71], v[6:7]
	v_mov_b64_e32 v[68:69], v[4:5]
	v_mov_b64_e32 v[66:67], v[2:3]
	v_mov_b64_e32 v[64:65], v[0:1]
	v_mov_b64_e32 v[60:61], v[12:13]
	v_mov_b64_e32 v[58:59], v[10:11]
	v_mov_b64_e32 v[56:57], v[8:9]
	v_mov_b64_e32 v[54:55], v[6:7]
	v_mov_b64_e32 v[52:53], v[4:5]
	v_mov_b64_e32 v[50:51], v[2:3]
	v_mov_b64_e32 v[48:49], v[0:1]
	v_mov_b64_e32 v[44:45], v[12:13]
	v_mov_b64_e32 v[42:43], v[10:11]
	v_mov_b64_e32 v[40:41], v[8:9]
	v_mov_b64_e32 v[38:39], v[6:7]
	v_mov_b64_e32 v[36:37], v[4:5]
	v_mov_b64_e32 v[34:35], v[2:3]
	v_mov_b64_e32 v[32:33], v[0:1]
	v_mov_b64_e32 v[28:29], v[12:13]
	v_mov_b64_e32 v[26:27], v[10:11]
	v_mov_b64_e32 v[24:25], v[8:9]
	v_mov_b64_e32 v[22:23], v[6:7]
	v_mov_b64_e32 v[20:21], v[4:5]
	v_mov_b64_e32 v[18:19], v[2:3]
	v_mov_b64_e32 v[16:17], v[0:1]
	s_sub_i32 s24, s46, 0x12000
	s_lshl_b32 s24, s24, 4
	s_add_i32 s24, s24, 0x12800
	v_mbcnt_lo_u32_b32 v0, -1, 0
	v_mbcnt_hi_u32_b32 v0, -1, v0
	v_lshl_add_u32 v0, v0, 2, s24
	ds_write_b32 v0, v226
	ds_write_b32 v0, v227 offset:256
	ds_write_b32 v0, v228 offset:512
	ds_write_b32 v0, v229 offset:768
	ds_write_b32 v0, v230 offset:1024
	ds_write_b32 v0, v231 offset:1280
	ds_write_b32 v0, v232 offset:1536
	ds_write_b32 v0, v233 offset:1792
	ds_write_b32 v0, v234 offset:2048
	ds_write_b32 v0, v235 offset:2304
	ds_write_b32 v0, v236 offset:2560
	ds_write_b32 v0, v238 offset:2816
	ds_write_b32 v0, v239 offset:3072
	ds_write_b32 v0, v240 offset:3328
	ds_write_b32 v0, v241 offset:3584
	ds_write_b32 v0, v247 offset:3840
	s_waitcnt lgkmcnt(0)
	v_mov_b32_e32 v247, v237
	v_sub_f32_e32 v226, 0, v249
	v_sub_f32_e32 v227, 0, v249
	v_sub_f32_e32 v228, 0, v249
	v_sub_f32_e32 v229, 0, v249
	v_sub_f32_e32 v230, 0, v249
	v_sub_f32_e32 v231, 0, v249
	v_sub_f32_e32 v232, 0, v249
	v_sub_f32_e32 v233, 0, v249
	v_sub_f32_e32 v234, 0, v249
	v_sub_f32_e32 v235, 0, v249
	v_sub_f32_e32 v236, 0, v249
	v_sub_f32_e32 v237, 0, v249
	v_sub_f32_e32 v238, 0, v249
	v_sub_f32_e32 v239, 0, v249
	v_sub_f32_e32 v240, 0, v249
	v_sub_f32_e32 v241, 0, v249
.LBB0_1989:
	s_lshl_b32 s20, s20, 1
	v_add_u32_e32 v0, s20, v251
	ds_read_b64_tr_b16 v[208:209], v0 offset:24576
	ds_read_b64_tr_b16 v[210:211], v0 offset:25088
	s_waitcnt lgkmcnt(9)
	v_mfma_f32_32x32x16_bf16 v[128:143], v[204:207], v[172:175], v[226:241]
	v_add_f32_e32 v2, v96, v97
	v_add_f32_e32 v2, v98, v2
	v_add_f32_e32 v2, v99, v2
	v_add_f32_e32 v2, v100, v2
	v_add_f32_e32 v2, v101, v2
	v_cvt_pk_bf16_f32 v160, v96, v97
	v_cvt_pk_bf16_f32 v161, v98, v99
	ds_read_b64_tr_b16 v[204:205], v0 offset:28672
	ds_read_b64_tr_b16 v[206:207], v0 offset:29184
	s_waitcnt lgkmcnt(10)
	v_mfma_f32_32x32x16_bf16 v[112:127], v[196:199], v[172:175], v[226:241]
	v_add_f32_e32 v2, v102, v2
	v_add_f32_e32 v2, v103, v2
	v_add_f32_e32 v2, v104, v2
	v_add_f32_e32 v2, v105, v2
	v_cvt_pk_bf16_f32 v162, v100, v101
	v_cvt_pk_bf16_f32 v163, v102, v103
	ds_read_b64_tr_b16 v[10:11], v0 offset:25600
	ds_read_b64_tr_b16 v[12:13], v0 offset:26112
	s_waitcnt lgkmcnt(11)
	v_mfma_f32_32x32x16_bf16 v[128:143], v[200:203], v[168:171], v[128:143]
	v_add_f32_e32 v2, v106, v2
	v_add_f32_e32 v2, v107, v2
	v_add_f32_e32 v2, v108, v2
	v_add_f32_e32 v2, v109, v2
	v_cvt_pk_bf16_f32 v152, v104, v105
	v_cvt_pk_bf16_f32 v153, v106, v107
	ds_read_b64_tr_b16 v[6:7], v0 offset:29696
	ds_read_b64_tr_b16 v[8:9], v0 offset:30208
	s_waitcnt lgkmcnt(12)
	v_mfma_f32_32x32x16_bf16 v[112:127], v[192:195], v[168:171], v[112:127]
	v_add_f32_e32 v2, v110, v2
	v_add_f32_e32 v2, v111, v2
	v_add_f32_e32 v2, v80, v2
	v_add_f32_e32 v14, v81, v2
	v_cvt_pk_bf16_f32 v154, v108, v109
	v_cvt_pk_bf16_f32 v155, v110, v111
	ds_read_b64_tr_b16 v[2:3], v0 offset:26624
	ds_read_b64_tr_b16 v[4:5], v0 offset:27136
	s_waitcnt lgkmcnt(13)
	v_mfma_f32_32x32x16_bf16 v[128:143], v[188:191], v[164:167], v[128:143]
	v_add_f32_e32 v14, v82, v14
	v_add_f32_e32 v14, v83, v14
	v_add_f32_e32 v14, v84, v14
	v_add_f32_e32 v14, v85, v14
	v_cvt_pk_bf16_f32 v148, v80, v81
	v_cvt_pk_bf16_f32 v149, v82, v83
	ds_read_b64_tr_b16 v[100:101], v0 offset:30720
	ds_read_b64_tr_b16 v[102:103], v0 offset:31232
	s_waitcnt lgkmcnt(14)
	v_mfma_f32_32x32x16_bf16 v[112:127], v[184:187], v[164:167], v[112:127]
	v_add_f32_e32 v14, v86, v14
	v_add_f32_e32 v14, v87, v14
	v_add_f32_e32 v14, v88, v14
	v_add_f32_e32 v14, v89, v14
	v_cvt_pk_bf16_f32 v150, v84, v85
	v_cvt_pk_bf16_f32 v151, v86, v87
	ds_read_b64_tr_b16 v[96:97], v0 offset:27648
	ds_read_b64_tr_b16 v[98:99], v0 offset:28160
	s_waitcnt lgkmcnt(14)
	v_mfma_f32_32x32x16_bf16 v[128:143], v[180:183], v[156:159], v[128:143]
	v_add_f32_e32 v14, v90, v14
	v_add_f32_e32 v14, v91, v14
	v_add_f32_e32 v14, v92, v14
	v_add_f32_e32 v14, v93, v14
	v_cvt_pk_bf16_f32 v144, v88, v89
	v_cvt_pk_bf16_f32 v145, v90, v91
	ds_read_b64_tr_b16 v[88:89], v0 offset:31744
	ds_read_b64_tr_b16 v[90:91], v0 offset:32256
	v_mfma_f32_32x32x16_bf16 v[112:127], v[176:179], v[156:159], v[112:127]
	v_add_f32_e32 v14, v94, v14
	v_add_f32_e32 v14, v95, v14
	v_add_f32_e32 v82, 0, v14
	v_cvt_pk_bf16_f32 v146, v92, v93
	v_cvt_pk_bf16_f32 v147, v94, v95
	v_lshl_add_u64 v[14:15], v[220:221], 0, s[2:3]
	v_lshl_add_u64 v[80:81], v[14:15], 0, s[78:79]
	s_add_i32 s20, s29, s48
	v_lshl_add_u64 v[200:201], v[222:223], 0, s[2:3]
	s_mov_b64 s[30:31], 0x40000
	s_mov_b32 s21, m0
	s_mov_b32 m0, s20
	s_nop 0
	global_load_lds_dwordx4 v[80:81], off
	s_mov_b32 m0, s21
	v_lshl_add_u64 v[80:81], v[200:201], 0, s[30:31]
	s_lshl_b32 s20, s27, 1
	v_lshl_add_u64 v[202:203], v[224:225], 0, s[2:3]
	s_add_i32 s21, s20, s49
	s_mov_b32 s24, m0
	s_mov_b32 m0, s21
	s_nop 0
	global_load_lds_dwordx4 v[80:81], off
	s_mov_b32 m0, s24
	v_lshl_add_u64 v[80:81], v[202:203], 0, s[30:31]
	s_add_i32 s20, s20, s50
	s_mov_b32 s21, m0
	s_mov_b32 m0, s20
	s_nop 0
	global_load_lds_dwordx4 v[80:81], off
	s_mov_b32 m0, s21
	v_max_f32_e32 v80, v129, v129
	v_max_f32_e32 v81, v128, v128
	v_max_f32_e32 v80, v81, v80
	v_max3_f32 v81, v130, v131, v113
	v_max3_f32 v80, v80, v112, v114
	v_max3_f32 v80, v80, v115, v132
	v_max3_f32 v81, v81, v134, v135
	v_max3_f32 v80, v80, v133, v116
	v_max3_f32 v81, v81, v118, v119
	v_max3_f32 v80, v80, v117, v136
	v_max3_f32 v81, v81, v138, v139
	v_max3_f32 v80, v80, v137, v120
	v_max3_f32 v81, v81, v122, v123
	v_max3_f32 v80, v80, v121, v140
	v_max3_f32 v81, v81, v142, v143
	v_max3_f32 v80, v80, v141, v124
	v_max3_f32 v81, v81, v126, v127
	v_max3_f32 v80, v80, v125, v81
	v_mov_b32_e32 v81, v80
	s_nop 1
	v_permlane32_swap_b32_e32 v80, v81
	v_max_f32_e32 v81, v81, v81
	v_max_f32_e32 v80, v80, v80
	v_max_f32_e32 v80, v80, v81
	s_mov_b32 s20, 0x41000000
	v_cmp_lt_f32_e32 vcc, s20, v80
	s_cmp_lg_u64 vcc, 0
	v_add_f32_e32 v212, v247, v82
	s_cselect_b64 s[20:21], -1, 0
	s_cbranch_vccnz .LBB0_1997
.LBB0_1990:
	s_waitcnt lgkmcnt(14)
	v_mfma_f32_32x32x16_bf16 v[64:79], v[160:163], v[208:211], v[64:79]
	v_exp_f32_e32 v128, v128
	v_exp_f32_e32 v129, v129
	ds_read_b64_tr_b16 v[92:93], v0 offset:32768
	ds_read_b64_tr_b16 v[94:95], v0 offset:33280
	s_waitcnt lgkmcnt(14)
	v_mfma_f32_32x32x16_bf16 v[48:63], v[160:163], v[204:207], v[48:63]
	v_exp_f32_e32 v130, v130
	v_exp_f32_e32 v131, v131
	ds_read_b64_tr_b16 v[104:105], v0 offset:36864
	ds_read_b64_tr_b16 v[106:107], v0 offset:37376
	v_add_u32_e32 v196, s27, v250
	ds_read_b128 v[84:87], v196
	ds_read_b128 v[80:83], v196 offset:512
	s_waitcnt lgkmcnt(14)
	v_mfma_f32_32x32x16_bf16 v[64:79], v[152:155], v[10:13], v[64:79]
	v_exp_f32_e32 v132, v132
	v_exp_f32_e32 v133, v133
	ds_read_b64_tr_b16 v[108:109], v0 offset:33792
	ds_read_b64_tr_b16 v[110:111], v0 offset:34304
	ds_read_b128 v[184:187], v196 offset:2048
	ds_read_b128 v[176:179], v196 offset:2560
	v_mfma_f32_32x32x16_bf16 v[48:63], v[152:155], v[6:9], v[48:63]
	v_exp_f32_e32 v134, v134
	v_exp_f32_e32 v135, v135
	ds_read_b64_tr_b16 v[188:189], v0 offset:37888
	ds_read_b64_tr_b16 v[190:191], v0 offset:38400
	ds_read_b128 v[180:183], v196 offset:4096
	ds_read_b128 v[6:9], v196 offset:4608
	s_waitcnt lgkmcnt(14)
	v_mfma_f32_32x32x16_bf16 v[64:79], v[148:151], v[2:5], v[64:79]
	v_exp_f32_e32 v136, v136
	v_exp_f32_e32 v137, v137
	ds_read_b64_tr_b16 v[192:193], v0 offset:34816
	ds_read_b64_tr_b16 v[194:195], v0 offset:35328
	ds_read_b128 v[10:13], v196 offset:6144
	ds_read_b128 v[2:5], v196 offset:6656
	v_mfma_f32_32x32x16_bf16 v[48:63], v[148:151], v[100:103], v[48:63]
	v_exp_f32_e32 v138, v138
	v_exp_f32_e32 v139, v139
	ds_read_b64_tr_b16 v[100:101], v0 offset:38912
	ds_read_b64_tr_b16 v[102:103], v0 offset:39424
	v_mfma_f32_32x32x16_bf16 v[64:79], v[144:147], v[96:99], v[64:79]
	v_exp_f32_e32 v140, v140
	v_exp_f32_e32 v141, v141
	ds_read_b64_tr_b16 v[96:97], v0 offset:35840
	ds_read_b64_tr_b16 v[98:99], v0 offset:36352
	v_mfma_f32_32x32x16_bf16 v[48:63], v[144:147], v[88:91], v[48:63]
	v_exp_f32_e32 v142, v142
	v_exp_f32_e32 v143, v143
	ds_read_b64_tr_b16 v[88:89], v0 offset:39936
	ds_read_b64_tr_b16 v[90:91], v0 offset:40448
	s_waitcnt lgkmcnt(14)
	v_mfma_f32_32x32x16_bf16 v[32:47], v[160:163], v[92:95], v[32:47]
	v_exp_f32_e32 v112, v112
	v_exp_f32_e32 v113, v113
	v_mfma_f32_32x32x16_bf16 v[16:31], v[160:163], v[104:107], v[16:31]
	v_exp_f32_e32 v114, v114
	v_exp_f32_e32 v115, v115
	v_mfma_f32_32x32x16_bf16 v[32:47], v[152:155], v[108:111], v[32:47]
	v_exp_f32_e32 v116, v116
	v_exp_f32_e32 v117, v117
	s_waitcnt lgkmcnt(12)
	v_mfma_f32_32x32x16_bf16 v[16:31], v[152:155], v[188:191], v[16:31]
	v_exp_f32_e32 v118, v118
	v_exp_f32_e32 v119, v119
	s_waitcnt lgkmcnt(8)
	v_mfma_f32_32x32x16_bf16 v[32:47], v[148:151], v[192:195], v[32:47]
	v_exp_f32_e32 v120, v120
	v_exp_f32_e32 v121, v121
	s_waitcnt lgkmcnt(4)
	v_mfma_f32_32x32x16_bf16 v[16:31], v[148:151], v[100:103], v[16:31]
	v_exp_f32_e32 v122, v122
	v_exp_f32_e32 v123, v123
	s_waitcnt lgkmcnt(2)
	v_mfma_f32_32x32x16_bf16 v[32:47], v[144:147], v[96:99], v[32:47]
	v_exp_f32_e32 v124, v124
	v_exp_f32_e32 v125, v125
	s_waitcnt lgkmcnt(0)
	v_mfma_f32_32x32x16_bf16 v[16:31], v[144:147], v[88:91], v[16:31]
	v_exp_f32_e32 v126, v126
	v_exp_f32_e32 v127, v127
	s_waitcnt vmcnt(3) lgkmcnt(0)
	s_barrier
	s_andn2_b64 vcc, exec, s[20:21]
	v_add_u32_e32 v0, s46, v252
	s_cbranch_vccnz .LBB0_1992
	s_waitcnt lgkmcnt(0)
	ds_read_b128 v[88:91], v0 offset:96
	ds_read_b128 v[92:95], v0 offset:64
	ds_read_b128 v[96:99], v0 offset:32
	ds_read_b128 v[100:103], v0
	s_waitcnt lgkmcnt(3)
	v_pk_mul_f32 v[76:77], v[76:77], v[88:89]
	s_waitcnt lgkmcnt(2)
	v_pk_mul_f32 v[72:73], v[72:73], v[92:93]
	s_waitcnt lgkmcnt(1)
	v_pk_mul_f32 v[68:69], v[68:69], v[96:97]
	v_pk_mul_f32 v[78:79], v[78:79], v[90:91]
	v_pk_mul_f32 v[74:75], v[74:75], v[94:95]
	v_pk_mul_f32 v[70:71], v[70:71], v[98:99]
	s_waitcnt lgkmcnt(0)
	v_pk_mul_f32 v[66:67], v[66:67], v[102:103]
	v_pk_mul_f32 v[64:65], v[64:65], v[100:101]
	v_pk_mul_f32 v[60:61], v[60:61], v[88:89]
	v_pk_mul_f32 v[56:57], v[56:57], v[92:93]
	v_pk_mul_f32 v[52:53], v[52:53], v[96:97]
	v_pk_mul_f32 v[62:63], v[62:63], v[90:91]
	v_pk_mul_f32 v[58:59], v[58:59], v[94:95]
	v_pk_mul_f32 v[54:55], v[54:55], v[98:99]
	v_pk_mul_f32 v[50:51], v[50:51], v[102:103]
	v_pk_mul_f32 v[48:49], v[48:49], v[100:101]
	v_pk_mul_f32 v[44:45], v[44:45], v[88:89]
	v_pk_mul_f32 v[40:41], v[40:41], v[92:93]
	v_pk_mul_f32 v[36:37], v[36:37], v[96:97]
	v_pk_mul_f32 v[46:47], v[46:47], v[90:91]
	v_pk_mul_f32 v[42:43], v[42:43], v[94:95]
	v_pk_mul_f32 v[38:39], v[38:39], v[98:99]
	v_pk_mul_f32 v[34:35], v[34:35], v[102:103]
	v_pk_mul_f32 v[32:33], v[32:33], v[100:101]
	v_pk_mul_f32 v[28:29], v[28:29], v[88:89]
	v_pk_mul_f32 v[24:25], v[24:25], v[92:93]
	v_pk_mul_f32 v[20:21], v[20:21], v[96:97]
	v_pk_mul_f32 v[30:31], v[30:31], v[90:91]
	v_pk_mul_f32 v[26:27], v[26:27], v[94:95]
	v_pk_mul_f32 v[22:23], v[22:23], v[98:99]
	v_pk_mul_f32 v[18:19], v[18:19], v[102:103]
	v_pk_mul_f32 v[16:17], v[16:17], v[100:101]
.LBB0_1992:
	s_add_i32 s20, s27, 0x2000
	s_cmpk_lg_i32 s27, 0x4000
	s_cselect_b32 s52, s20, 0
	s_lshl_b32 s20, s29, 1
	v_add_u32_e32 v208, s20, v251
	ds_read_b64_tr_b16 v[196:197], v208 offset:24576
	ds_read_b64_tr_b16 v[198:199], v208 offset:25088
	v_mfma_f32_32x32x16_bf16 v[96:111], v[84:87], v[172:175], v[226:241]
	v_add_f32_e32 v88, v128, v129
	v_add_f32_e32 v88, v130, v88
	v_add_f32_e32 v88, v131, v88
	v_add_f32_e32 v88, v132, v88
	v_add_f32_e32 v88, v133, v88
	v_cvt_pk_bf16_f32 v160, v128, v129
	v_cvt_pk_bf16_f32 v161, v130, v131
	ds_read_b64_tr_b16 v[192:193], v208 offset:28672
	ds_read_b64_tr_b16 v[194:195], v208 offset:29184
	v_add_f32_e32 v84, v134, v88
	v_add_f32_e32 v84, v135, v84
	v_add_f32_e32 v84, v136, v84
	v_add_f32_e32 v128, v137, v84
	v_mfma_f32_32x32x16_bf16 v[80:95], v[80:83], v[172:175], v[226:241]
	v_cvt_pk_bf16_f32 v162, v132, v133
	v_cvt_pk_bf16_f32 v163, v134, v135
	ds_read_b64_tr_b16 v[188:189], v208 offset:25600
	ds_read_b64_tr_b16 v[190:191], v208 offset:26112
	v_mfma_f32_32x32x16_bf16 v[96:111], v[184:187], v[168:171], v[96:111]
	v_add_f32_e32 v128, v138, v128
	v_add_f32_e32 v128, v139, v128
	v_add_f32_e32 v128, v140, v128
	v_add_f32_e32 v128, v141, v128
	v_cvt_pk_bf16_f32 v152, v136, v137
	v_cvt_pk_bf16_f32 v153, v138, v139
	ds_read_b64_tr_b16 v[136:137], v208 offset:29696
	ds_read_b64_tr_b16 v[138:139], v208 offset:30208
	v_mfma_f32_32x32x16_bf16 v[80:95], v[176:179], v[168:171], v[80:95]
	v_add_f32_e32 v128, v142, v128
	v_add_f32_e32 v128, v143, v128
	v_add_f32_e32 v128, v112, v128
	v_add_f32_e32 v128, v113, v128
	v_cvt_pk_bf16_f32 v154, v140, v141
	v_cvt_pk_bf16_f32 v155, v142, v143
	ds_read_b64_tr_b16 v[132:133], v208 offset:26624
	ds_read_b64_tr_b16 v[134:135], v208 offset:27136
	v_mfma_f32_32x32x16_bf16 v[96:111], v[180:183], v[164:167], v[96:111]
	v_add_f32_e32 v128, v114, v128
	v_add_f32_e32 v128, v115, v128
	v_add_f32_e32 v128, v116, v128
	v_add_f32_e32 v140, v117, v128
	v_cvt_pk_bf16_f32 v148, v112, v113
	v_cvt_pk_bf16_f32 v149, v114, v115
	ds_read_b64_tr_b16 v[128:129], v208 offset:30720
	ds_read_b64_tr_b16 v[130:131], v208 offset:31232
	v_mfma_f32_32x32x16_bf16 v[80:95], v[6:9], v[164:167], v[80:95]
	v_add_f32_e32 v6, v118, v140
	v_add_f32_e32 v6, v119, v6
	v_add_f32_e32 v6, v120, v6
	v_add_f32_e32 v6, v121, v6
	v_cvt_pk_bf16_f32 v150, v116, v117
	v_cvt_pk_bf16_f32 v151, v118, v119
	ds_read_b64_tr_b16 v[112:113], v208 offset:27648
	ds_read_b64_tr_b16 v[114:115], v208 offset:28160
	v_mfma_f32_32x32x16_bf16 v[96:111], v[10:13], v[156:159], v[96:111]
	v_add_f32_e32 v6, v122, v6
	v_add_f32_e32 v6, v123, v6
	v_add_f32_e32 v6, v124, v6
	v_add_f32_e32 v10, v125, v6
	v_cvt_pk_bf16_f32 v144, v120, v121
	v_cvt_pk_bf16_f32 v145, v122, v123
	ds_read_b64_tr_b16 v[6:7], v208 offset:31744
	ds_read_b64_tr_b16 v[8:9], v208 offset:32256
	v_mfma_f32_32x32x16_bf16 v[80:95], v[2:5], v[156:159], v[80:95]
	v_add_f32_e32 v2, v126, v10
	v_add_f32_e32 v2, v127, v2
	v_add_f32_e32 v4, 0, v2
	v_cvt_pk_bf16_f32 v146, v124, v125
	v_cvt_pk_bf16_f32 v147, v126, v127
	s_mov_b64 s[20:21], 0xa0000
	v_lshl_add_u64 v[2:3], v[14:15], 0, s[20:21]
	s_add_i32 s20, s27, s48
	s_mov_b32 s21, m0
	s_mov_b32 m0, s20
	s_nop 0
	global_load_lds_dwordx4 v[2:3], off
	s_mov_b32 m0, s21
	v_lshl_add_u64 v[2:3], v[200:201], 0, s[56:57]
	s_lshl_b32 s20, s52, 1
	s_add_i32 s21, s20, s49
	s_mov_b32 s24, m0
	s_mov_b32 m0, s21
	s_nop 0
	global_load_lds_dwordx4 v[2:3], off
	s_mov_b32 m0, s24
	v_lshl_add_u64 v[2:3], v[202:203], 0, s[56:57]
	s_add_i32 s20, s20, s50
	s_mov_b32 s21, m0
	s_mov_b32 m0, s20
	s_nop 0
	global_load_lds_dwordx4 v[2:3], off
	s_mov_b32 m0, s21
	v_max_f32_e32 v2, v97, v97
	v_max_f32_e32 v3, v96, v96
	v_max_f32_e32 v2, v3, v2
	v_max3_f32 v3, v98, v99, v81
	v_max3_f32 v2, v2, v80, v82
	v_max3_f32 v2, v2, v83, v100
	v_max3_f32 v3, v3, v102, v103
	v_max3_f32 v2, v2, v101, v84
	v_max3_f32 v3, v3, v86, v87
	v_max3_f32 v2, v2, v85, v104
	v_max3_f32 v3, v3, v106, v107
	v_max3_f32 v2, v2, v105, v88
	v_max3_f32 v3, v3, v90, v91
	v_max3_f32 v2, v2, v89, v108
	v_max3_f32 v3, v3, v110, v111
	v_max3_f32 v2, v2, v109, v92
	v_max3_f32 v3, v3, v94, v95
	v_max3_f32 v2, v2, v93, v3
	v_mov_b32_e32 v3, v2
	s_nop 1
	v_permlane32_swap_b32_e32 v2, v3
	v_max_f32_e32 v3, v3, v3
	v_max_f32_e32 v2, v2, v2
	v_max_f32_e32 v2, v2, v3
	s_mov_b32 s20, 0x41000000
	v_cmp_lt_f32_e32 vcc, s20, v2
	s_cmp_lg_u64 vcc, 0
	v_add_f32_e32 v247, v212, v4
	s_cselect_b64 s[20:21], -1, 0
	s_cbranch_vccnz .LBB0_2000
.LBB0_1993:
	s_waitcnt lgkmcnt(14)
	v_mfma_f32_32x32x16_bf16 v[64:79], v[160:163], v[196:199], v[64:79]
	v_exp_f32_e32 v96, v96
	v_exp_f32_e32 v97, v97
	ds_read_b64_tr_b16 v[2:3], v208 offset:32768
	ds_read_b64_tr_b16 v[4:5], v208 offset:33280
	s_waitcnt lgkmcnt(14)
	v_mfma_f32_32x32x16_bf16 v[48:63], v[160:163], v[192:195], v[48:63]
	v_exp_f32_e32 v98, v98
	v_exp_f32_e32 v99, v99
	ds_read_b64_tr_b16 v[10:11], v208 offset:36864
	ds_read_b64_tr_b16 v[12:13], v208 offset:37376
	v_add_u32_e32 v14, s52, v250
	ds_read_b128 v[204:207], v14
	ds_read_b128 v[196:199], v14 offset:512
	s_waitcnt lgkmcnt(14)
	v_mfma_f32_32x32x16_bf16 v[64:79], v[152:155], v[188:191], v[64:79]
	v_exp_f32_e32 v100, v100
	v_exp_f32_e32 v101, v101
	ds_read_b64_tr_b16 v[116:117], v208 offset:33792
	ds_read_b64_tr_b16 v[118:119], v208 offset:34304
	ds_read_b128 v[200:203], v14 offset:2048
	ds_read_b128 v[192:195], v14 offset:2560
	v_mfma_f32_32x32x16_bf16 v[48:63], v[152:155], v[136:139], v[48:63]
	v_exp_f32_e32 v102, v102
	v_exp_f32_e32 v103, v103
	ds_read_b64_tr_b16 v[120:121], v208 offset:37888
	ds_read_b64_tr_b16 v[122:123], v208 offset:38400
	ds_read_b128 v[188:191], v14 offset:4096
	ds_read_b128 v[184:187], v14 offset:4608
	s_waitcnt lgkmcnt(14)
	v_mfma_f32_32x32x16_bf16 v[64:79], v[148:151], v[132:135], v[64:79]
	v_exp_f32_e32 v104, v104
	v_exp_f32_e32 v105, v105
	ds_read_b64_tr_b16 v[124:125], v208 offset:34816
	ds_read_b64_tr_b16 v[126:127], v208 offset:35328
	ds_read_b128 v[180:183], v14 offset:6144
	ds_read_b128 v[176:179], v14 offset:6656
	v_mfma_f32_32x32x16_bf16 v[48:63], v[148:151], v[128:131], v[48:63]
	v_exp_f32_e32 v106, v106
	v_exp_f32_e32 v107, v107
	ds_read_b64_tr_b16 v[128:129], v208 offset:38912
	ds_read_b64_tr_b16 v[130:131], v208 offset:39424
	v_mfma_f32_32x32x16_bf16 v[64:79], v[144:147], v[112:115], v[64:79]
	v_exp_f32_e32 v108, v108
	v_exp_f32_e32 v109, v109
	ds_read_b64_tr_b16 v[112:113], v208 offset:35840
	ds_read_b64_tr_b16 v[114:115], v208 offset:36352
	v_mfma_f32_32x32x16_bf16 v[48:63], v[144:147], v[6:9], v[48:63]
	v_exp_f32_e32 v110, v110
	v_exp_f32_e32 v111, v111
	ds_read_b64_tr_b16 v[6:7], v208 offset:39936
	ds_read_b64_tr_b16 v[8:9], v208 offset:40448
	s_waitcnt lgkmcnt(14)
	v_mfma_f32_32x32x16_bf16 v[32:47], v[160:163], v[2:5], v[32:47]
	v_exp_f32_e32 v80, v80
	v_exp_f32_e32 v81, v81
	v_mfma_f32_32x32x16_bf16 v[16:31], v[160:163], v[10:13], v[16:31]
	v_exp_f32_e32 v82, v82
	v_exp_f32_e32 v83, v83
	v_mfma_f32_32x32x16_bf16 v[32:47], v[152:155], v[116:119], v[32:47]
	v_exp_f32_e32 v84, v84
	v_exp_f32_e32 v85, v85
	s_waitcnt lgkmcnt(12)
	v_mfma_f32_32x32x16_bf16 v[16:31], v[152:155], v[120:123], v[16:31]
	v_exp_f32_e32 v86, v86
	v_exp_f32_e32 v87, v87
	s_waitcnt lgkmcnt(8)
	v_mfma_f32_32x32x16_bf16 v[32:47], v[148:151], v[124:127], v[32:47]
	v_exp_f32_e32 v88, v88
	v_exp_f32_e32 v89, v89
	s_waitcnt lgkmcnt(4)
	v_mfma_f32_32x32x16_bf16 v[16:31], v[148:151], v[128:131], v[16:31]
	v_exp_f32_e32 v90, v90
	v_exp_f32_e32 v91, v91
	s_waitcnt lgkmcnt(2)
	v_mfma_f32_32x32x16_bf16 v[32:47], v[144:147], v[112:115], v[32:47]
	v_exp_f32_e32 v92, v92
	v_exp_f32_e32 v93, v93
	s_waitcnt lgkmcnt(0)
	v_mfma_f32_32x32x16_bf16 v[16:31], v[144:147], v[6:9], v[16:31]
	v_exp_f32_e32 v94, v94
	v_exp_f32_e32 v95, v95
	s_waitcnt vmcnt(3) lgkmcnt(0)
	s_barrier
	s_andn2_b64 vcc, exec, s[20:21]
	s_cbranch_vccnz .LBB0_1995
	s_waitcnt lgkmcnt(0)
	ds_read_b128 v[2:5], v0 offset:96
	ds_read_b128 v[6:9], v0 offset:64
	ds_read_b128 v[10:13], v0 offset:32
	ds_read_b128 v[112:115], v0
	s_waitcnt lgkmcnt(3)
	v_pk_mul_f32 v[76:77], v[76:77], v[2:3]
	s_waitcnt lgkmcnt(2)
	v_pk_mul_f32 v[72:73], v[72:73], v[6:7]
	s_waitcnt lgkmcnt(1)
	v_pk_mul_f32 v[68:69], v[68:69], v[10:11]
	v_pk_mul_f32 v[78:79], v[78:79], v[4:5]
	v_pk_mul_f32 v[74:75], v[74:75], v[8:9]
	v_pk_mul_f32 v[70:71], v[70:71], v[12:13]
	s_waitcnt lgkmcnt(0)
	v_pk_mul_f32 v[66:67], v[66:67], v[114:115]
	v_pk_mul_f32 v[64:65], v[64:65], v[112:113]
	v_pk_mul_f32 v[60:61], v[60:61], v[2:3]
	v_pk_mul_f32 v[56:57], v[56:57], v[6:7]
	v_pk_mul_f32 v[52:53], v[52:53], v[10:11]
	v_pk_mul_f32 v[62:63], v[62:63], v[4:5]
	v_pk_mul_f32 v[58:59], v[58:59], v[8:9]
	v_pk_mul_f32 v[54:55], v[54:55], v[12:13]
	v_pk_mul_f32 v[50:51], v[50:51], v[114:115]
	v_pk_mul_f32 v[48:49], v[48:49], v[112:113]
	v_pk_mul_f32 v[44:45], v[44:45], v[2:3]
	v_pk_mul_f32 v[40:41], v[40:41], v[6:7]
	v_pk_mul_f32 v[36:37], v[36:37], v[10:11]
	v_pk_mul_f32 v[46:47], v[46:47], v[4:5]
	v_pk_mul_f32 v[42:43], v[42:43], v[8:9]
	v_pk_mul_f32 v[38:39], v[38:39], v[12:13]
	v_pk_mul_f32 v[34:35], v[34:35], v[114:115]
	v_pk_mul_f32 v[32:33], v[32:33], v[112:113]
	v_pk_mul_f32 v[28:29], v[28:29], v[2:3]
	v_pk_mul_f32 v[24:25], v[24:25], v[6:7]
	v_pk_mul_f32 v[20:21], v[20:21], v[10:11]
	v_pk_mul_f32 v[30:31], v[30:31], v[4:5]
	v_pk_mul_f32 v[26:27], v[26:27], v[8:9]
	v_pk_mul_f32 v[22:23], v[22:23], v[12:13]
	v_pk_mul_f32 v[18:19], v[18:19], v[114:115]
	v_pk_mul_f32 v[16:17], v[16:17], v[112:113]

.Lnegm_exit:
	v_mov_b32_e32 v237, v247
	s_sub_i32 s24, s46, 0x12000
	s_lshl_b32 s24, s24, 4
	s_add_i32 s24, s24, 0x12800
	v_mbcnt_lo_u32_b32 v247, -1, 0
	v_mbcnt_hi_u32_b32 v247, -1, v247
	v_lshl_add_u32 v247, v247, 2, s24
	ds_read_b32 v226, v247
	ds_read_b32 v227, v247 offset:256
	ds_read_b32 v228, v247 offset:512
	ds_read_b32 v229, v247 offset:768
	ds_read_b32 v230, v247 offset:1024
	ds_read_b32 v231, v247 offset:1280
	ds_read_b32 v232, v247 offset:1536
	ds_read_b32 v233, v247 offset:1792
	ds_read_b32 v234, v247 offset:2048
	ds_read_b32 v235, v247 offset:2304
	ds_read_b32 v236, v247 offset:2560
	ds_read_b32 v238, v247 offset:2816
	ds_read_b32 v239, v247 offset:3072
	ds_read_b32 v240, v247 offset:3328
	ds_read_b32 v241, v247 offset:3584
	ds_read_b32 v247, v247 offset:3840
	s_waitcnt lgkmcnt(0)
	s_branch .LBB0_2005
.LBB0_1997:
	v_max_f32_e32 v80, v80, v80
	v_max_f32_e32 v81, 0, v80
	v_exp_f32_e64 v80, -v81
	s_and_saveexec_b64 s[24:25], s[18:19]
	ds_write_b32 v246, v80
	s_or_b64 exec, exec, s[24:25]
	v_add_f32_e32 v249, v249, v81
	v_sub_f32_e32 v128, v128, v81
	v_sub_f32_e32 v129, v129, v81
	v_sub_f32_e32 v130, v130, v81
	v_sub_f32_e32 v131, v131, v81
	v_sub_f32_e32 v132, v132, v81
	v_sub_f32_e32 v133, v133, v81
	v_sub_f32_e32 v134, v134, v81
	v_sub_f32_e32 v135, v135, v81
	v_sub_f32_e32 v136, v136, v81
	v_sub_f32_e32 v137, v137, v81
	v_sub_f32_e32 v138, v138, v81
	v_sub_f32_e32 v139, v139, v81
	v_sub_f32_e32 v140, v140, v81
	v_sub_f32_e32 v141, v141, v81
	v_sub_f32_e32 v142, v142, v81
	v_sub_f32_e32 v143, v143, v81
	v_sub_f32_e32 v112, v112, v81
	v_sub_f32_e32 v113, v113, v81
	v_sub_f32_e32 v114, v114, v81
	v_sub_f32_e32 v115, v115, v81
	v_sub_f32_e32 v116, v116, v81
	v_sub_f32_e32 v117, v117, v81
	v_sub_f32_e32 v118, v118, v81
	v_sub_f32_e32 v119, v119, v81
	v_sub_f32_e32 v120, v120, v81
	v_sub_f32_e32 v121, v121, v81
	v_sub_f32_e32 v122, v122, v81
	v_sub_f32_e32 v123, v123, v81
	v_sub_f32_e32 v124, v124, v81
	v_sub_f32_e32 v125, v125, v81
	v_sub_f32_e32 v126, v126, v81
	v_sub_f32_e32 v127, v127, v81
	v_sub_f32_e32 v226, v226, v81
	v_sub_f32_e32 v227, v227, v81
	v_sub_f32_e32 v228, v228, v81
	v_sub_f32_e32 v229, v229, v81
	v_sub_f32_e32 v230, v230, v81
	v_sub_f32_e32 v231, v231, v81
	v_sub_f32_e32 v232, v232, v81
	v_sub_f32_e32 v233, v233, v81
	v_sub_f32_e32 v234, v234, v81
	v_sub_f32_e32 v235, v235, v81
	v_sub_f32_e32 v236, v236, v81
	v_sub_f32_e32 v237, v237, v81
	v_sub_f32_e32 v238, v238, v81
	v_sub_f32_e32 v239, v239, v81
	v_sub_f32_e32 v240, v240, v81
	v_sub_f32_e32 v241, v241, v81
	v_mul_f32_e32 v212, v212, v80
	s_branch .LBB0_1990
.LBB0_2000:
	v_max_f32_e32 v2, v2, v2
	v_max_f32_e32 v3, 0, v2
	v_exp_f32_e64 v2, -v3
	s_and_saveexec_b64 s[24:25], s[18:19]
	ds_write_b32 v246, v2
	s_or_b64 exec, exec, s[24:25]
	v_add_f32_e32 v249, v249, v3
	v_sub_f32_e32 v96, v96, v3
	v_sub_f32_e32 v97, v97, v3
	v_sub_f32_e32 v98, v98, v3
	v_sub_f32_e32 v99, v99, v3
	v_sub_f32_e32 v100, v100, v3
	v_sub_f32_e32 v101, v101, v3
	v_sub_f32_e32 v102, v102, v3
	v_sub_f32_e32 v103, v103, v3
	v_sub_f32_e32 v104, v104, v3
	v_sub_f32_e32 v105, v105, v3
	v_sub_f32_e32 v106, v106, v3
	v_sub_f32_e32 v107, v107, v3
	v_sub_f32_e32 v108, v108, v3
	v_sub_f32_e32 v109, v109, v3
	v_sub_f32_e32 v110, v110, v3
	v_sub_f32_e32 v111, v111, v3
	v_sub_f32_e32 v80, v80, v3
	v_sub_f32_e32 v81, v81, v3
	v_sub_f32_e32 v82, v82, v3
	v_sub_f32_e32 v83, v83, v3
	v_sub_f32_e32 v84, v84, v3
	v_sub_f32_e32 v85, v85, v3
	v_sub_f32_e32 v86, v86, v3
	v_sub_f32_e32 v87, v87, v3
	v_sub_f32_e32 v88, v88, v3
	v_sub_f32_e32 v89, v89, v3
	v_sub_f32_e32 v90, v90, v3
	v_sub_f32_e32 v91, v91, v3
	v_sub_f32_e32 v92, v92, v3
	v_sub_f32_e32 v93, v93, v3
	v_sub_f32_e32 v94, v94, v3
	v_sub_f32_e32 v95, v95, v3
	v_sub_f32_e32 v226, v226, v3
	v_sub_f32_e32 v227, v227, v3
	v_sub_f32_e32 v228, v228, v3
	v_sub_f32_e32 v229, v229, v3
	v_sub_f32_e32 v230, v230, v3
	v_sub_f32_e32 v231, v231, v3
	v_sub_f32_e32 v232, v232, v3
	v_sub_f32_e32 v233, v233, v3
	v_sub_f32_e32 v234, v234, v3
	v_sub_f32_e32 v235, v235, v3
	v_sub_f32_e32 v236, v236, v3
	v_sub_f32_e32 v237, v237, v3
	v_sub_f32_e32 v238, v238, v3
	v_sub_f32_e32 v239, v239, v3
	v_sub_f32_e32 v240, v240, v3
	v_sub_f32_e32 v241, v241, v3
	v_mul_f32_e32 v247, v247, v2
	s_branch .LBB0_1993

.LBB0_2206:
	s_waitcnt vmcnt(0)
	s_barrier
	s_getreg_b32 s0, hwreg(HW_REG_HW_ID, 0, 7)
	s_and_b32 s0, s0, 63
	s_lshl_b32 s0, s0, 2
	s_add_i32 s0, s0, 0x22240
	v_mov_b32_e32 v0, s0
	ds_read_b32 v0, v0
	v_mbcnt_lo_u32_b32 v2, -1, 0
	v_mbcnt_hi_u32_b32 v2, -1, v2
	s_waitcnt lgkmcnt(0)
	v_lshl_or_b32 v0, v0, 6, v2
	v_cmp_eq_u32_e32 vcc, 0, v0
	s_and_saveexec_b64 s[0:1], vcc
	v_readlane_b32 s14, v253, 12
	v_readlane_b32 s15, v253, 13
	s_branch .LBB0_2260
	v_readlane_b32 s2, v253, 23
	s_waitcnt vmcnt(0) expcnt(0) lgkmcnt(0)
	s_nop 0
	v_mov_b32_e32 v0, s2
	ds_read_b32 v2, v0
	v_readlane_b32 s2, v253, 24
	s_waitcnt lgkmcnt(0)
	v_cmp_eq_u32_e32 vcc, 0, v2
	v_mov_b32_e32 v0, s2
	ds_read_b32 v0, v0
	s_cbranch_vccnz .LBB0_2209
	s_lshl_b32 s20, s74, 6
	s_cbranch_execz .LBB0_2210
	s_branch .LBB0_2224
